# resid epilogue: modulated-activation (next GEMM A operand) stores write-through
# speedup vs baseline: 1.0232x; 1.0052x over previous
.LBB0_952:
	v_lshlrev_b64 v[2:3], 1, v[0:1]
	v_cvt_pk_bf16_f32 v118, v52, v53
	v_cvt_pk_bf16_f32 v119, v54, v55
	v_cvt_pk_bf16_f32 v120, v56, v57
	v_cvt_pk_bf16_f32 v121, v58, v59
	v_lshl_add_u64 v[112:113], s[10:11], 0, v[2:3]
	v_mbcnt_lo_u32_b32 v112, -1, 0
	v_mbcnt_hi_u32_b32 v112, -1, v112
	v_lshl_add_u32 v112, v112, 4, s99
	ds_write_b128 v112, v[118:121]
	v_lshl_add_u64 v[2:3], s[78:79], 0, v[2:3]
	v_pk_fma_f32 v[112:113], v[54:55], v[30:31], v[22:23]
	v_pk_fma_f32 v[118:119], v[52:53], v[28:29], v[20:21]
	v_pk_fma_f32 v[120:121], v[56:57], v[44:45], v[24:25]
	v_pk_fma_f32 v[122:123], v[58:59], v[46:47], v[26:27]
	v_cvt_pk_bf16_f32 v118, v118, v119
	v_cvt_pk_bf16_f32 v119, v112, v113
	v_cvt_pk_bf16_f32 v120, v120, v121
	s_nop 0
	v_cvt_pk_bf16_f32 v121, v122, v123
	global_store_dwordx4 v[2:3], v[118:121], off sc1
	s_branch .LBB0_954

.LBB0_957:
	v_lshlrev_b64 v[2:3], 1, v[0:1]
	v_cvt_pk_bf16_f32 v118, v52, v53
	v_cvt_pk_bf16_f32 v119, v54, v55
	v_cvt_pk_bf16_f32 v120, v56, v57
	v_cvt_pk_bf16_f32 v121, v58, v59
	v_lshl_add_u64 v[122:123], s[10:11], 0, v[2:3]
	v_mbcnt_lo_u32_b32 v122, -1, 0
	v_mbcnt_hi_u32_b32 v122, -1, v122
	v_lshl_add_u32 v122, v122, 4, s99
	ds_write_b128 v122, v[118:121] offset:1024
	v_lshl_add_u64 v[2:3], s[78:79], 0, v[2:3]
	s_nop 0
	v_pk_fma_f32 v[120:121], v[54:55], v[42:43], v[34:35]
	v_pk_fma_f32 v[118:119], v[52:53], v[40:41], v[32:33]
	v_pk_fma_f32 v[122:123], v[58:59], v[50:51], v[38:39]
	v_pk_fma_f32 v[124:125], v[56:57], v[48:49], v[36:37]
	v_cvt_pk_bf16_f32 v118, v118, v119
	v_cvt_pk_bf16_f32 v119, v120, v121
	v_cvt_pk_bf16_f32 v121, v122, v123
	s_nop 0
	v_cvt_pk_bf16_f32 v120, v124, v125
	global_store_dwordx4 v[2:3], v[118:121], off sc1
	s_branch .LBB0_959

.LBB0_962:
	v_lshlrev_b64 v[2:3], 1, v[0:1]
	v_cvt_pk_bf16_f32 v118, v24, v25
	v_cvt_pk_bf16_f32 v119, v26, v27
	v_cvt_pk_bf16_f32 v120, v56, v57
	v_cvt_pk_bf16_f32 v121, v58, v59
	v_lshl_add_u64 v[122:123], s[10:11], 0, v[2:3]
	v_mbcnt_lo_u32_b32 v122, -1, 0
	v_mbcnt_hi_u32_b32 v122, -1, v122
	v_lshl_add_u32 v122, v122, 4, s99
	ds_write_b128 v122, v[118:121] offset:2048
	v_lshl_add_u64 v[2:3], s[78:79], 0, v[2:3]
	s_nop 0
	v_pk_fma_f32 v[120:121], v[26:27], v[46:47], v[22:23]
	v_pk_fma_f32 v[118:119], v[24:25], v[44:45], v[20:21]
	v_pk_fma_f32 v[122:123], v[58:59], v[54:55], v[30:31]
	v_pk_fma_f32 v[124:125], v[56:57], v[52:53], v[28:29]
	v_cvt_pk_bf16_f32 v118, v118, v119
	v_cvt_pk_bf16_f32 v119, v120, v121
	v_cvt_pk_bf16_f32 v121, v122, v123
	s_nop 0
	v_cvt_pk_bf16_f32 v120, v124, v125
	global_store_dwordx4 v[2:3], v[118:121], off sc1
	s_branch .LBB0_964

.LBB0_967:
	v_lshlrev_b64 v[2:3], 1, v[0:1]
	v_cvt_pk_bf16_f32 v120, v48, v49
	v_cvt_pk_bf16_f32 v121, v50, v51
	v_cvt_pk_bf16_f32 v122, v56, v57
	v_cvt_pk_bf16_f32 v123, v58, v59
	v_lshl_add_u64 v[124:125], s[10:11], 0, v[2:3]
	v_mov_b32_e32 v244, v120
	v_mov_b32_e32 v245, v121
	v_mov_b32_e32 v250, v122
	v_mov_b32_e32 v251, v123
	v_lshl_add_u64 v[2:3], s[78:79], 0, v[2:3]
	s_nop 0
	v_pk_fma_f32 v[122:123], v[50:51], v[38:39], v[26:27]
	v_pk_fma_f32 v[120:121], v[48:49], v[36:37], v[24:25]
	v_pk_fma_f32 v[124:125], v[58:59], v[42:43], v[34:35]
	v_pk_fma_f32 v[130:131], v[56:57], v[40:41], v[32:33]
	v_cvt_pk_bf16_f32 v120, v120, v121
	v_cvt_pk_bf16_f32 v121, v122, v123
	v_cvt_pk_bf16_f32 v123, v124, v125
	s_nop 0
	v_cvt_pk_bf16_f32 v122, v130, v131
	global_store_dwordx4 v[2:3], v[120:123], off sc1
	s_branch .LBB0_969

.LBB0_972:
	v_lshlrev_b64 v[2:3], 1, v[0:1]
	v_cvt_pk_bf16_f32 v120, v52, v53
	v_cvt_pk_bf16_f32 v121, v54, v55
	v_cvt_pk_bf16_f32 v122, v56, v57
	v_cvt_pk_bf16_f32 v123, v58, v59
	v_lshl_add_u64 v[116:117], s[10:11], 0, v[2:3]
	v_mov_b32_e32 v221, v120
	v_mov_b32_e32 v223, v121
	v_mov_b32_e32 v252, v122
	v_mov_b32_e32 v253, v123
	v_lshl_add_u64 v[2:3], s[78:79], 0, v[2:3]
	s_nop 0
	v_pk_fma_f32 v[120:121], v[52:53], v[44:45], v[28:29]
	v_pk_fma_f32 v[122:123], v[56:57], v[48:49], v[20:21]
	v_pk_fma_f32 v[116:117], v[54:55], v[46:47], v[30:31]
	v_pk_fma_f32 v[124:125], v[58:59], v[50:51], v[22:23]
	v_cvt_pk_bf16_f32 v120, v120, v121
	v_cvt_pk_bf16_f32 v121, v116, v117
	v_cvt_pk_bf16_f32 v122, v122, v123
	s_nop 0
	v_cvt_pk_bf16_f32 v123, v124, v125
	global_store_dwordx4 v[2:3], v[120:123], off sc1
	s_branch .LBB0_974

.LBB0_977:
	v_lshlrev_b64 v[2:3], 1, v[0:1]
	v_cvt_pk_bf16_f32 v8, v12, v13
	v_cvt_pk_bf16_f32 v9, v14, v15
	v_cvt_pk_bf16_f32 v10, v4, v5
	v_cvt_pk_bf16_f32 v11, v6, v7
	v_lshl_add_u64 v[16:17], s[10:11], 0, v[2:3]
	global_store_dwordx4 v[16:17], v[8:11], off
	v_lshl_add_u64 v[2:3], s[78:79], 0, v[2:3]
	s_nop 0
	v_pk_fma_f32 v[10:11], v[14:15], v[46:47], v[30:31]
	v_pk_fma_f32 v[8:9], v[12:13], v[44:45], v[28:29]
	v_pk_fma_f32 v[16:17], v[6:7], v[50:51], v[22:23]
	v_pk_fma_f32 v[18:19], v[4:5], v[48:49], v[20:21]
	v_cvt_pk_bf16_f32 v8, v8, v9
	v_cvt_pk_bf16_f32 v9, v10, v11
	v_cvt_pk_bf16_f32 v11, v16, v17
	s_nop 0
	v_cvt_pk_bf16_f32 v10, v18, v19
	global_store_dwordx4 v[2:3], v[8:11], off sc1
	s_branch .LBB0_979

.LBB0_991:
	v_lshlrev_b64 v[2:3], 1, v[0:1]
	v_cvt_pk_bf16_f32 v100, v52, v53
	v_cvt_pk_bf16_f32 v101, v54, v55
	v_cvt_pk_bf16_f32 v102, v56, v57
	v_cvt_pk_bf16_f32 v103, v58, v59
	v_lshl_add_u64 v[104:105], s[10:11], 0, v[2:3]
	v_mov_b32_e32 v228, v100
	v_mov_b32_e32 v229, v101
	v_mov_b32_e32 v230, v102
	v_mov_b32_e32 v231, v103
	v_lshl_add_u64 v[2:3], s[78:79], 0, v[2:3]
	s_nop 0
	v_pk_fma_f32 v[102:103], v[54:55], v[38:39], v[22:23]
	v_pk_fma_f32 v[100:101], v[52:53], v[36:37], v[20:21]
	v_pk_fma_f32 v[104:105], v[58:59], v[46:47], v[30:31]
	v_pk_fma_f32 v[106:107], v[56:57], v[44:45], v[28:29]
	v_cvt_pk_bf16_f32 v100, v100, v101
	v_cvt_pk_bf16_f32 v101, v102, v103
	v_cvt_pk_bf16_f32 v103, v104, v105
	s_nop 0
	v_cvt_pk_bf16_f32 v102, v106, v107
	global_store_dwordx4 v[2:3], v[100:103], off sc1
	s_branch .LBB0_993

.LBB0_996:
	v_lshlrev_b64 v[2:3], 1, v[0:1]
	v_cvt_pk_bf16_f32 v92, v52, v53
	v_cvt_pk_bf16_f32 v93, v54, v55
	v_cvt_pk_bf16_f32 v94, v56, v57
	v_cvt_pk_bf16_f32 v95, v58, v59
	v_lshl_add_u64 v[96:97], s[10:11], 0, v[2:3]
	v_mov_b32_e32 v232, v92
	v_mov_b32_e32 v233, v93
	v_mov_b32_e32 v234, v94
	v_mov_b32_e32 v235, v95
	v_lshl_add_u64 v[2:3], s[78:79], 0, v[2:3]
	s_nop 0
	v_pk_fma_f32 v[94:95], v[54:55], v[42:43], v[26:27]
	v_pk_fma_f32 v[92:93], v[52:53], v[40:41], v[24:25]
	v_pk_fma_f32 v[96:97], v[58:59], v[50:51], v[34:35]
	v_pk_fma_f32 v[100:101], v[56:57], v[48:49], v[32:33]
	v_cvt_pk_bf16_f32 v92, v92, v93
	v_cvt_pk_bf16_f32 v93, v94, v95
	v_cvt_pk_bf16_f32 v95, v96, v97
	s_nop 0
	v_cvt_pk_bf16_f32 v94, v100, v101
	global_store_dwordx4 v[2:3], v[92:95], off sc1
	s_branch .LBB0_998

.LBB0_1001:
	v_lshlrev_b64 v[2:3], 1, v[0:1]
	v_cvt_pk_bf16_f32 v84, v52, v53
	v_cvt_pk_bf16_f32 v85, v54, v55
	v_cvt_pk_bf16_f32 v86, v56, v57
	v_cvt_pk_bf16_f32 v87, v58, v59
	v_lshl_add_u64 v[88:89], s[10:11], 0, v[2:3]
	v_mov_b32_e32 v236, v84
	v_mov_b32_e32 v237, v85
	v_mov_b32_e32 v238, v86
	v_mov_b32_e32 v239, v87
	v_lshl_add_u64 v[2:3], s[78:79], 0, v[2:3]
	s_nop 0
	v_pk_fma_f32 v[86:87], v[54:55], v[38:39], v[22:23]
	v_pk_fma_f32 v[84:85], v[52:53], v[36:37], v[20:21]
	v_pk_fma_f32 v[88:89], v[58:59], v[46:47], v[30:31]
	v_pk_fma_f32 v[90:91], v[56:57], v[44:45], v[28:29]
	v_cvt_pk_bf16_f32 v84, v84, v85
	v_cvt_pk_bf16_f32 v85, v86, v87
	v_cvt_pk_bf16_f32 v87, v88, v89
	s_nop 0
	v_cvt_pk_bf16_f32 v86, v90, v91
	global_store_dwordx4 v[2:3], v[84:87], off sc1
	s_branch .LBB0_1003

.LBB0_1006:
	v_lshlrev_b64 v[2:3], 1, v[0:1]
	v_cvt_pk_bf16_f32 v76, v52, v53
	v_cvt_pk_bf16_f32 v77, v54, v55
	v_cvt_pk_bf16_f32 v78, v56, v57
	v_cvt_pk_bf16_f32 v79, v58, v59
	v_lshl_add_u64 v[80:81], s[10:11], 0, v[2:3]
	v_mov_b32_e32 v224, v76
	v_mov_b32_e32 v225, v77
	v_mov_b32_e32 v226, v78
	v_mov_b32_e32 v227, v79
	v_lshl_add_u64 v[2:3], s[78:79], 0, v[2:3]
	s_nop 0
	v_pk_fma_f32 v[78:79], v[54:55], v[42:43], v[26:27]
	v_pk_fma_f32 v[76:77], v[52:53], v[40:41], v[24:25]
	v_pk_fma_f32 v[80:81], v[58:59], v[50:51], v[34:35]
	v_pk_fma_f32 v[82:83], v[56:57], v[48:49], v[32:33]
	v_cvt_pk_bf16_f32 v76, v76, v77
	v_cvt_pk_bf16_f32 v77, v78, v79
	v_cvt_pk_bf16_f32 v79, v80, v81
	s_nop 0
	v_cvt_pk_bf16_f32 v78, v82, v83
	global_store_dwordx4 v[2:3], v[76:79], off sc1
	s_branch .LBB0_1008

.LBB0_1011:
	v_lshlrev_b64 v[2:3], 1, v[0:1]
	v_cvt_pk_bf16_f32 v68, v52, v53
	v_cvt_pk_bf16_f32 v69, v54, v55
	v_cvt_pk_bf16_f32 v70, v56, v57
	v_cvt_pk_bf16_f32 v71, v58, v59
	v_lshl_add_u64 v[72:73], s[10:11], 0, v[2:3]
	v_readlane_b32 s100, v68, 63
	v_readlane_b32 s101, v69, 63
	v_mbcnt_lo_u32_b32 v72, -1, 0
	v_mbcnt_hi_u32_b32 v72, -1, v72
	v_writelane_b32 v255, s100, 46
	v_writelane_b32 v255, s101, 47
	v_readlane_b32 s100, v70, 63
	v_readlane_b32 s101, v71, 63
	v_lshl_add_u32 v72, v72, 4, s99
	s_nop 0
	v_writelane_b32 v255, s100, 48
	v_writelane_b32 v255, s101, 49
	s_bitset0_b64 exec, 63
	ds_write_b128 v72, v[68:71] offset:3072
	s_mov_b64 exec, -1
	v_lshl_add_u64 v[2:3], s[78:79], 0, v[2:3]
	s_nop 0
	v_pk_fma_f32 v[70:71], v[54:55], v[38:39], v[30:31]
	v_pk_fma_f32 v[68:69], v[52:53], v[36:37], v[28:29]
	v_pk_fma_f32 v[72:73], v[58:59], v[46:47], v[22:23]
	v_pk_fma_f32 v[74:75], v[56:57], v[44:45], v[20:21]
	v_cvt_pk_bf16_f32 v68, v68, v69
	v_cvt_pk_bf16_f32 v69, v70, v71
	v_cvt_pk_bf16_f32 v71, v72, v73
	s_nop 0
	v_cvt_pk_bf16_f32 v70, v74, v75
	global_store_dwordx4 v[2:3], v[68:71], off sc1
	s_branch .LBB0_1013

.LBB0_1016:
	v_lshlrev_b64 v[2:3], 1, v[0:1]
	v_cvt_pk_bf16_f32 v8, v12, v13
	v_cvt_pk_bf16_f32 v9, v14, v15
	v_cvt_pk_bf16_f32 v10, v4, v5
	v_cvt_pk_bf16_f32 v11, v6, v7
	v_lshl_add_u64 v[16:17], s[10:11], 0, v[2:3]
	v_mov_b32_e32 v240, v8
	v_mov_b32_e32 v241, v9
	v_mov_b32_e32 v242, v10
	v_mov_b32_e32 v243, v11
	v_lshl_add_u64 v[2:3], s[78:79], 0, v[2:3]
	s_nop 0
	v_pk_fma_f32 v[10:11], v[14:15], v[38:39], v[30:31]
	v_pk_fma_f32 v[8:9], v[12:13], v[36:37], v[28:29]
	v_pk_fma_f32 v[16:17], v[6:7], v[46:47], v[22:23]
	v_pk_fma_f32 v[18:19], v[4:5], v[44:45], v[20:21]
	v_cvt_pk_bf16_f32 v8, v8, v9
	v_cvt_pk_bf16_f32 v9, v10, v11
	v_cvt_pk_bf16_f32 v11, v16, v17
	s_nop 0
	v_cvt_pk_bf16_f32 v10, v18, v19
	global_store_dwordx4 v[2:3], v[8:11], off sc1
	s_branch .LBB0_1018
